# E25: prompt-FoX exp/PV section: 56 packed v_pk_add_f32 split into scalar v_sub/v_add (bit-identical); on E23
# baseline (speedup 1.0000x reference)
.LBB0_1395:
	v_sub_f32_e32 v10, v86, v158
	v_sub_f32_e32 v11, v87, v158
	v_sub_f32_e32 v4, v82, v158
	v_sub_f32_e32 v5, v83, v158
	v_exp_f32_e32 v168, v10
	v_exp_f32_e32 v169, v11
	v_sub_f32_e32 v10, v88, v158
	v_sub_f32_e32 v11, v89, v158
	v_sub_f32_e32 v6, v84, v158
	v_sub_f32_e32 v7, v85, v158
	v_exp_f32_e32 v170, v10
	v_exp_f32_e32 v171, v11
	v_sub_f32_e32 v10, v90, v158
	v_sub_f32_e32 v11, v91, v158
	v_exp_f32_e32 v4, v4
	v_exp_f32_e32 v160, v10
	v_exp_f32_e32 v161, v11
	v_sub_f32_e32 v10, v92, v158
	v_sub_f32_e32 v11, v93, v158
	v_exp_f32_e32 v5, v5
	v_exp_f32_e32 v162, v10
	v_exp_f32_e32 v163, v11
	v_sub_f32_e32 v10, v94, v158
	v_sub_f32_e32 v11, v95, v158
	v_add3_u32 v2, s70, v193, v194
	v_exp_f32_e32 v164, v10
	v_exp_f32_e32 v165, v11
	v_sub_f32_e32 v10, v96, v158
	v_sub_f32_e32 v11, v97, v158
	v_exp_f32_e32 v6, v6
	v_exp_f32_e32 v166, v10
	v_exp_f32_e32 v167, v11
	v_sub_f32_e32 v10, v50, v158
	v_sub_f32_e32 v11, v51, v158
	v_exp_f32_e32 v7, v7
	v_exp_f32_e32 v90, v10
	v_exp_f32_e32 v91, v11
	v_sub_f32_e32 v10, v52, v158
	v_sub_f32_e32 v11, v53, v158
	v_add_f32_e32 v8, 0, v4
	v_add_f32_e32 v9, 0, v5
	v_exp_f32_e32 v92, v10
	v_exp_f32_e32 v93, v11
	v_sub_f32_e32 v10, v54, v158
	v_sub_f32_e32 v11, v55, v158
	v_add_f32_e32 v8, v6, v8
	v_add_f32_e32 v9, v7, v9
	v_exp_f32_e32 v94, v10
	v_exp_f32_e32 v95, v11
	v_sub_f32_e32 v10, v56, v158
	v_sub_f32_e32 v11, v57, v158
	v_cvt_pk_bf16_f32 v4, v4, v5
	v_exp_f32_e32 v96, v10
	v_exp_f32_e32 v97, v11
	v_sub_f32_e32 v10, v58, v158
	v_sub_f32_e32 v11, v59, v158
	v_cvt_pk_bf16_f32 v5, v6, v7
	v_exp_f32_e32 v82, v10
	v_exp_f32_e32 v83, v11
	v_sub_f32_e32 v10, v60, v158
	v_sub_f32_e32 v11, v61, v158
	v_cvt_pk_bf16_f32 v6, v168, v169
	v_exp_f32_e32 v84, v10
	v_exp_f32_e32 v85, v11
	v_sub_f32_e32 v10, v62, v158
	v_sub_f32_e32 v11, v63, v158
	v_cvt_pk_bf16_f32 v7, v170, v171
	v_exp_f32_e32 v86, v10
	v_exp_f32_e32 v87, v11
	v_sub_f32_e32 v10, v64, v158
	v_sub_f32_e32 v11, v65, v158
	v_add_f32_e32 v8, v168, v8
	v_add_f32_e32 v9, v169, v9
	v_exp_f32_e32 v88, v10
	v_exp_f32_e32 v89, v11
	v_sub_f32_e32 v10, v66, v158
	v_sub_f32_e32 v11, v67, v158
	v_add_f32_e32 v8, v170, v8
	v_add_f32_e32 v9, v171, v9
	v_exp_f32_e32 v66, v10
	v_exp_f32_e32 v67, v11
	v_sub_f32_e32 v10, v68, v158
	v_sub_f32_e32 v11, v69, v158
	v_add_f32_e32 v8, v160, v8
	v_add_f32_e32 v9, v161, v9
	v_exp_f32_e32 v68, v10
	v_exp_f32_e32 v69, v11
	v_sub_f32_e32 v10, v70, v158
	v_sub_f32_e32 v11, v71, v158
	v_add_f32_e32 v8, v162, v8
	v_add_f32_e32 v9, v163, v9
	v_exp_f32_e32 v70, v10
	v_exp_f32_e32 v71, v11
	v_sub_f32_e32 v10, v72, v158
	v_sub_f32_e32 v11, v73, v158
	v_add_f32_e32 v8, v164, v8
	v_add_f32_e32 v9, v165, v9
	v_exp_f32_e32 v72, v10
	v_exp_f32_e32 v73, v11
	v_sub_f32_e32 v10, v74, v158
	v_sub_f32_e32 v11, v75, v158
	v_add_f32_e32 v8, v166, v8
	v_add_f32_e32 v9, v167, v9
	v_exp_f32_e32 v58, v10
	v_exp_f32_e32 v59, v11
	v_sub_f32_e32 v10, v76, v158
	v_sub_f32_e32 v11, v77, v158
	ds_read_b64_tr_b16 v[74:75], v2 offset:18432
	ds_read_b64_tr_b16 v[76:77], v2 offset:19968
	s_waitcnt lgkmcnt(0)
	v_mfma_f32_32x32x16_bf16 v[34:49], v[74:77], v[4:7], v[34:49]
	ds_read_b64_tr_b16 v[74:75], v2 offset:18496
	ds_read_b64_tr_b16 v[76:77], v2 offset:20032
	v_add_f32_e64 v8, v90, v8
	v_add_f32_e64 v9, v91, v9
	v_exp_f32_e32 v60, v10
	v_add_f32_e32 v8, v92, v8
	v_add_f32_e32 v9, v93, v9
	v_exp_f32_e32 v61, v11
	v_add_f32_e32 v8, v94, v8
	v_add_f32_e32 v9, v95, v9
	v_sub_f32_e32 v10, v78, v158
	v_sub_f32_e32 v11, v79, v158
	s_waitcnt lgkmcnt(0)
	v_mfma_f32_32x32x16_bf16 v[18:33], v[74:77], v[4:7], v[18:33]
	ds_read_b64_tr_b16 v[74:75], v2 offset:21504
	ds_read_b64_tr_b16 v[76:77], v2 offset:23040
	v_cvt_pk_bf16_f32 v4, v160, v161
	v_cvt_pk_bf16_f32 v5, v162, v163
	v_cvt_pk_bf16_f32 v6, v164, v165
	v_cvt_pk_bf16_f32 v7, v166, v167
	v_add_f32_e32 v8, v96, v8
	v_add_f32_e32 v9, v97, v9
	v_exp_f32_e32 v62, v10
	s_waitcnt lgkmcnt(0)
	v_mfma_f32_32x32x16_bf16 v[34:49], v[74:77], v[4:7], v[34:49]
	ds_read_b64_tr_b16 v[74:75], v2 offset:21568
	ds_read_b64_tr_b16 v[76:77], v2 offset:23104
	v_add_f32_e64 v8, v82, v8
	v_add_f32_e64 v9, v83, v9
	v_exp_f32_e32 v63, v11
	v_add_f32_e32 v8, v84, v8
	v_add_f32_e32 v9, v85, v9
	v_sub_f32_e32 v10, v80, v158
	v_sub_f32_e32 v11, v81, v158
	v_add_f32_e32 v8, v86, v8
	v_add_f32_e32 v9, v87, v9
	v_exp_f32_e32 v64, v10
	s_waitcnt lgkmcnt(0)
	v_mfma_f32_32x32x16_bf16 v[18:33], v[74:77], v[4:7], v[18:33]
	ds_read_b64_tr_b16 v[74:75], v2 offset:24576
	ds_read_b64_tr_b16 v[76:77], v2 offset:26112
	v_cvt_pk_bf16_f32 v4, v90, v91
	v_cvt_pk_bf16_f32 v5, v92, v93
	v_cvt_pk_bf16_f32 v6, v94, v95
	v_cvt_pk_bf16_f32 v7, v96, v97
	v_add_f32_e32 v8, v88, v8
	v_add_f32_e32 v9, v89, v9
	v_exp_f32_e32 v65, v11
	s_waitcnt lgkmcnt(0)
	v_mfma_f32_32x32x16_bf16 v[34:49], v[74:77], v[4:7], v[34:49]
	ds_read_b64_tr_b16 v[74:75], v2 offset:24640
	ds_read_b64_tr_b16 v[76:77], v2 offset:26176
	v_add_f32_e64 v8, v66, v8
	v_add_f32_e64 v9, v67, v9
	v_add_f32_e64 v10, v98, -v158
	v_add_f32_e64 v11, v99, -v158
	v_add_f32_e32 v8, v68, v8
	v_add_f32_e32 v9, v69, v9
	v_exp_f32_e32 v50, v10
	v_add_f32_e32 v8, v70, v8
	v_add_f32_e32 v9, v71, v9
	v_exp_f32_e32 v51, v11
	s_waitcnt lgkmcnt(0)
	v_mfma_f32_32x32x16_bf16 v[18:33], v[74:77], v[4:7], v[18:33]
	ds_read_b64_tr_b16 v[74:75], v2 offset:27648
	ds_read_b64_tr_b16 v[76:77], v2 offset:29184
	v_cvt_pk_bf16_f32 v4, v82, v83
	v_cvt_pk_bf16_f32 v5, v84, v85
	v_cvt_pk_bf16_f32 v6, v86, v87
	v_cvt_pk_bf16_f32 v7, v88, v89
	v_add_f32_e32 v8, v72, v8
	v_add_f32_e32 v9, v73, v9
	v_sub_f32_e32 v10, v100, v158
	v_sub_f32_e32 v11, v101, v158
	s_waitcnt lgkmcnt(0)
	v_mfma_f32_32x32x16_bf16 v[34:49], v[74:77], v[4:7], v[34:49]
	ds_read_b64_tr_b16 v[74:75], v2 offset:27712
	ds_read_b64_tr_b16 v[76:77], v2 offset:29248
	v_add_f32_e64 v8, v58, v8
	v_add_f32_e64 v9, v59, v9
	v_exp_f32_e32 v52, v10
	v_add_f32_e32 v8, v60, v8
	v_add_f32_e32 v9, v61, v9
	v_exp_f32_e32 v53, v11
	v_add_f32_e32 v8, v62, v8
	v_add_f32_e32 v9, v63, v9
	v_sub_f32_e32 v10, v102, v158
	v_sub_f32_e32 v11, v103, v158
	s_waitcnt lgkmcnt(0)
	v_mfma_f32_32x32x16_bf16 v[18:33], v[74:77], v[4:7], v[18:33]
	v_cvt_pk_bf16_f32 v4, v66, v67
	v_cvt_pk_bf16_f32 v5, v68, v69
	ds_read_b64_tr_b16 v[66:67], v2 offset:30720
	ds_read_b64_tr_b16 v[68:69], v2 offset:32256
	v_cvt_pk_bf16_f32 v6, v70, v71
	v_cvt_pk_bf16_f32 v7, v72, v73
	v_add_f32_e32 v8, v64, v8
	v_add_f32_e32 v9, v65, v9
	v_exp_f32_e32 v54, v10
	s_waitcnt lgkmcnt(0)
	v_mfma_f32_32x32x16_bf16 v[34:49], v[66:69], v[4:7], v[34:49]
	ds_read_b64_tr_b16 v[66:67], v2 offset:30784
	ds_read_b64_tr_b16 v[68:69], v2 offset:32320
	v_add_f32_e64 v8, v50, v8
	v_add_f32_e64 v9, v51, v9
	v_exp_f32_e32 v55, v11
	v_sub_f32_e32 v10, v104, v158
	v_sub_f32_e32 v11, v105, v158
	v_add_f32_e32 v8, v52, v8
	v_add_f32_e32 v9, v53, v9
	v_exp_f32_e32 v56, v10
	v_exp_f32_e32 v57, v11
	s_waitcnt lgkmcnt(0)
	v_mfma_f32_32x32x16_bf16 v[18:33], v[66:69], v[4:7], v[18:33]
	v_cvt_pk_bf16_f32 v4, v58, v59
	v_cvt_pk_bf16_f32 v5, v60, v61
	ds_read_b64_tr_b16 v[58:59], v2 offset:33792
	ds_read_b64_tr_b16 v[60:61], v2 offset:35328
	v_cvt_pk_bf16_f32 v6, v62, v63
	v_cvt_pk_bf16_f32 v7, v64, v65
	v_sub_f32_e32 v10, v106, v158
	v_sub_f32_e32 v11, v107, v158
	v_sub_f32_e32 v12, v108, v158
	v_sub_f32_e32 v13, v109, v158
	s_waitcnt lgkmcnt(0)
	v_mfma_f32_32x32x16_bf16 v[34:49], v[58:61], v[4:7], v[34:49]
	ds_read_b64_tr_b16 v[58:59], v2 offset:33856
	ds_read_b64_tr_b16 v[60:61], v2 offset:35392
	v_exp_f32_e32 v10, v10
	v_exp_f32_e32 v11, v11
	v_exp_f32_e32 v12, v12
	v_exp_f32_e32 v13, v13
	v_add_f32_e32 v8, v54, v8
	v_add_f32_e32 v9, v55, v9
	v_sub_f32_e32 v14, v110, v158
	v_sub_f32_e32 v15, v111, v158
	s_waitcnt lgkmcnt(0)
	v_mfma_f32_32x32x16_bf16 v[18:33], v[58:61], v[4:7], v[18:33]
	v_cvt_pk_bf16_f32 v4, v50, v51
	v_cvt_pk_bf16_f32 v5, v52, v53
	ds_read_b64_tr_b16 v[50:51], v2 offset:36864
	ds_read_b64_tr_b16 v[52:53], v2 offset:38400
	v_cvt_pk_bf16_f32 v6, v54, v55
	v_cvt_pk_bf16_f32 v7, v56, v57
	v_add_f32_e32 v8, v56, v8
	v_add_f32_e32 v9, v57, v9
	v_sub_f32_e32 v16, v112, v158
	v_sub_f32_e32 v17, v113, v158
	s_waitcnt lgkmcnt(0)
	v_mfma_f32_32x32x16_bf16 v[34:49], v[50:53], v[4:7], v[34:49]
	ds_read_b64_tr_b16 v[50:51], v2 offset:36928
	ds_read_b64_tr_b16 v[52:53], v2 offset:38464
	v_add_f32_e64 v8, v10, v8
	v_add_f32_e64 v9, v11, v9
	v_exp_f32_e32 v14, v14
	v_add_f32_e32 v8, v12, v8
	v_add_f32_e32 v9, v13, v9
	v_exp_f32_e32 v15, v15
	v_exp_f32_e32 v16, v16
	v_exp_f32_e32 v17, v17
	s_waitcnt lgkmcnt(0)
	v_mfma_f32_32x32x16_bf16 v[18:33], v[50:53], v[4:7], v[18:33]
	v_cvt_pk_bf16_f32 v4, v10, v11
	v_cvt_pk_bf16_f32 v5, v12, v13
	ds_read_b64_tr_b16 v[10:11], v2 offset:39936
	ds_read_b64_tr_b16 v[12:13], v2 offset:41472
	v_cvt_pk_bf16_f32 v6, v14, v15
	v_cvt_pk_bf16_f32 v7, v16, v17
	v_add_f32_e32 v8, v14, v8
	v_add_f32_e32 v9, v15, v9
	s_waitcnt lgkmcnt(0)
	v_mfma_f32_32x32x16_bf16 v[34:49], v[10:13], v[4:7], v[34:49]
	ds_read_b64_tr_b16 v[10:11], v2 offset:40000
	ds_read_b64_tr_b16 v[12:13], v2 offset:41536
	v_add_f32_e64 v8, v16, v8
	v_add_f32_e64 v9, v17, v9
	v_add_f32_e32 v2, v8, v9
	v_add_f32_e32 v192, v192, v2
	s_waitcnt lgkmcnt(0)
	v_mfma_f32_32x32x16_bf16 v[18:33], v[10:13], v[4:7], v[18:33]
